# scan: yd reduction deferred to a transposed 16x16 DPP reduce per chunk, S update rewritten as U=S*W+KX*V then S=U-BB*sa (shorter chain, 25 instr per step)
# speedup vs baseline: 1.0604x; 1.0326x over previous
.LBB0_65:
	s_bitcmp1_b32 s40, 0
	s_cselect_b32 s2, 0x5500, 0
	v_lshl_or_b32 v94, v93, 2, s2
	v_lshl_add_u32 v95, v0, 2, s2
	v_mov_b32_e32 v96, s2
	v_mul_u32_u24_e32 v46, 0x154, v93
	v_add_u32_e32 v47, v46, v96
	v_add_u32_e32 v46, v46, v95
	ds_read_b64 v[44:45], v47 offset:1344
	ds_read_b32 v48, v46 offset:1280
	ds_read_b128 v[110:113], v94
	ds_read_b128 v[126:129], v94 offset:1024
	ds_read_b128 v[114:117], v94 offset:256
	ds_read_b128 v[118:121], v94 offset:512
	ds_read_b128 v[122:125], v94 offset:768
	ds_read_b32 v130, v95 offset:1280
	s_mov_b64 s[2:3], 0x100
	s_mov_b64 s[20:21], 0x800
	s_waitcnt lgkmcnt(4)
	v_pk_mul_f32 v[24:25], v[30:31], v[112:113]
	v_pk_mul_f32 v[26:27], v[30:31], v[128:129]
	v_pk_fma_f32 v[24:25], v[28:29], v[110:111], v[24:25]
	v_pk_fma_f32 v[26:27], v[28:29], v[126:127], v[26:27]
	v_add_f32_e32 v34, v24, v25
	ds_read_b128 v[134:137], v94 offset:1360
	v_add_f32_e32 v50, v26, v27
	v_add_f32_dpp v34, v34, v34 quad_perm:[1,0,3,2] row_mask:0xf bank_mask:0xf bound_ctrl:1
	ds_read_b128 v[150:153], v94 offset:2384
	ds_read_b128 v[138:141], v94 offset:1616
	v_add_f32_dpp v34, v34, v34 quad_perm:[2,3,0,1] row_mask:0xf bank_mask:0xf bound_ctrl:1
	s_waitcnt lgkmcnt(3)
	v_pk_mul_f32 v[36:37], v[122:123], v[130:131] op_sel_hi:[1,0]
	v_pk_mul_f32 v[38:39], v[124:125], v[130:131] op_sel_hi:[1,0]
	v_add_f32_dpp v34, v34, v34 row_ror:4 row_mask:0xf bank_mask:0xf bound_ctrl:1
	v_pk_fma_f32 v[36:37], v[28:29], v[118:119], v[36:37]
	v_pk_fma_f32 v[38:39], v[30:31], v[120:121], v[38:39]
	v_add_f32_dpp v34, v34, v34 row_ror:8 row_mask:0xf bank_mask:0xf bound_ctrl:1
	ds_read_b128 v[142:145], v94 offset:1872
	ds_read_b128 v[146:149], v94 offset:2128
	v_pk_fma_f32 v[28:29], v[114:115], v[34:35], v[36:37] op_sel_hi:[1,0,1] neg_lo:[0,1,0] neg_hi:[0,1,0]
	v_pk_fma_f32 v[30:31], v[116:117], v[34:35], v[38:39] op_sel_hi:[1,0,1] neg_lo:[0,1,0] neg_hi:[0,1,0]
	v_cndmask_b32_e64 v42, 0, v34, s[30:31]
	ds_read_b32 v154, v95 offset:2640
	s_waitcnt lgkmcnt(4)
	v_pk_mul_f32 v[24:25], v[30:31], v[136:137]
	v_pk_mul_f32 v[26:27], v[30:31], v[152:153]
	v_pk_fma_f32 v[24:25], v[28:29], v[134:135], v[24:25]
	v_pk_fma_f32 v[26:27], v[28:29], v[150:151], v[26:27]
	v_add_f32_e32 v34, v24, v25
	ds_read_b128 v[110:113], v94 offset:2720
	v_add_f32_e32 v51, v26, v27
	v_add_f32_dpp v34, v34, v34 quad_perm:[1,0,3,2] row_mask:0xf bank_mask:0xf bound_ctrl:1
	ds_read_b128 v[126:129], v94 offset:3744
	ds_read_b128 v[114:117], v94 offset:2976
	v_add_f32_dpp v34, v34, v34 quad_perm:[2,3,0,1] row_mask:0xf bank_mask:0xf bound_ctrl:1
	s_waitcnt lgkmcnt(3)
	v_pk_mul_f32 v[36:37], v[146:147], v[154:155] op_sel_hi:[1,0]
	v_pk_mul_f32 v[38:39], v[148:149], v[154:155] op_sel_hi:[1,0]
	v_add_f32_dpp v34, v34, v34 row_ror:4 row_mask:0xf bank_mask:0xf bound_ctrl:1
	v_pk_fma_f32 v[36:37], v[28:29], v[142:143], v[36:37]
	v_pk_fma_f32 v[38:39], v[30:31], v[144:145], v[38:39]
	v_add_f32_dpp v34, v34, v34 row_ror:8 row_mask:0xf bank_mask:0xf bound_ctrl:1
	ds_read_b128 v[118:121], v94 offset:3232
	ds_read_b128 v[122:125], v94 offset:3488
	v_pk_fma_f32 v[28:29], v[138:139], v[34:35], v[36:37] op_sel_hi:[1,0,1] neg_lo:[0,1,0] neg_hi:[0,1,0]
	v_pk_fma_f32 v[30:31], v[140:141], v[34:35], v[38:39] op_sel_hi:[1,0,1] neg_lo:[0,1,0] neg_hi:[0,1,0]
	v_cndmask_b32_e64 v42, v42, v34, s[70:71]
	ds_read_b32 v130, v95 offset:4000
	s_waitcnt lgkmcnt(4)
	v_pk_mul_f32 v[24:25], v[30:31], v[112:113]
	v_pk_mul_f32 v[26:27], v[30:31], v[128:129]
	v_pk_fma_f32 v[24:25], v[28:29], v[110:111], v[24:25]
	v_pk_fma_f32 v[26:27], v[28:29], v[126:127], v[26:27]
	v_add_f32_e32 v34, v24, v25
	ds_read_b128 v[134:137], v94 offset:4080
	v_add_f32_e32 v52, v26, v27
	v_add_f32_dpp v34, v34, v34 quad_perm:[1,0,3,2] row_mask:0xf bank_mask:0xf bound_ctrl:1
	ds_read_b128 v[150:153], v94 offset:5104
	ds_read_b128 v[138:141], v94 offset:4336
	v_add_f32_dpp v34, v34, v34 quad_perm:[2,3,0,1] row_mask:0xf bank_mask:0xf bound_ctrl:1
	s_waitcnt lgkmcnt(3)
	v_pk_mul_f32 v[36:37], v[122:123], v[130:131] op_sel_hi:[1,0]
	v_pk_mul_f32 v[38:39], v[124:125], v[130:131] op_sel_hi:[1,0]
	v_add_f32_dpp v34, v34, v34 row_ror:4 row_mask:0xf bank_mask:0xf bound_ctrl:1
	v_pk_fma_f32 v[36:37], v[28:29], v[118:119], v[36:37]
	v_pk_fma_f32 v[38:39], v[30:31], v[120:121], v[38:39]
	v_add_f32_dpp v34, v34, v34 row_ror:8 row_mask:0xf bank_mask:0xf bound_ctrl:1
	ds_read_b128 v[142:145], v94 offset:4592
	ds_read_b128 v[146:149], v94 offset:4848
	v_pk_fma_f32 v[28:29], v[114:115], v[34:35], v[36:37] op_sel_hi:[1,0,1] neg_lo:[0,1,0] neg_hi:[0,1,0]
	v_pk_fma_f32 v[30:31], v[116:117], v[34:35], v[38:39] op_sel_hi:[1,0,1] neg_lo:[0,1,0] neg_hi:[0,1,0]
	v_cndmask_b32_e64 v42, v42, v34, s[72:73]
	ds_read_b32 v154, v95 offset:5360
	s_waitcnt lgkmcnt(4)
	v_pk_mul_f32 v[24:25], v[30:31], v[136:137]
	v_pk_mul_f32 v[26:27], v[30:31], v[152:153]
	v_pk_fma_f32 v[24:25], v[28:29], v[134:135], v[24:25]
	v_pk_fma_f32 v[26:27], v[28:29], v[150:151], v[26:27]
	v_add_f32_e32 v34, v24, v25
	ds_read_b128 v[110:113], v94 offset:5440
	v_add_f32_e32 v53, v26, v27
	v_add_f32_dpp v34, v34, v34 quad_perm:[1,0,3,2] row_mask:0xf bank_mask:0xf bound_ctrl:1
	ds_read_b128 v[126:129], v94 offset:6464
	ds_read_b128 v[114:117], v94 offset:5696
	v_add_f32_dpp v34, v34, v34 quad_perm:[2,3,0,1] row_mask:0xf bank_mask:0xf bound_ctrl:1
	s_waitcnt lgkmcnt(3)
	v_pk_mul_f32 v[36:37], v[146:147], v[154:155] op_sel_hi:[1,0]
	v_pk_mul_f32 v[38:39], v[148:149], v[154:155] op_sel_hi:[1,0]
	v_add_f32_dpp v34, v34, v34 row_ror:4 row_mask:0xf bank_mask:0xf bound_ctrl:1
	v_pk_fma_f32 v[36:37], v[28:29], v[142:143], v[36:37]
	v_pk_fma_f32 v[38:39], v[30:31], v[144:145], v[38:39]
	v_add_f32_dpp v34, v34, v34 row_ror:8 row_mask:0xf bank_mask:0xf bound_ctrl:1
	ds_read_b128 v[118:121], v94 offset:5952
	ds_read_b128 v[122:125], v94 offset:6208
	v_pk_fma_f32 v[28:29], v[138:139], v[34:35], v[36:37] op_sel_hi:[1,0,1] neg_lo:[0,1,0] neg_hi:[0,1,0]
	v_pk_fma_f32 v[30:31], v[140:141], v[34:35], v[38:39] op_sel_hi:[1,0,1] neg_lo:[0,1,0] neg_hi:[0,1,0]
	v_cndmask_b32_e64 v42, v42, v34, s[74:75]
	ds_read_b32 v130, v95 offset:6720
	s_waitcnt lgkmcnt(4)
	v_pk_mul_f32 v[24:25], v[30:31], v[112:113]
	v_pk_mul_f32 v[26:27], v[30:31], v[128:129]
	v_pk_fma_f32 v[24:25], v[28:29], v[110:111], v[24:25]
	v_pk_fma_f32 v[26:27], v[28:29], v[126:127], v[26:27]
	v_add_f32_e32 v34, v24, v25
	ds_read_b128 v[134:137], v94 offset:6800
	v_add_f32_e32 v54, v26, v27
	v_add_f32_dpp v34, v34, v34 quad_perm:[1,0,3,2] row_mask:0xf bank_mask:0xf bound_ctrl:1
	ds_read_b128 v[150:153], v94 offset:7824
	ds_read_b128 v[138:141], v94 offset:7056
	v_add_f32_dpp v34, v34, v34 quad_perm:[2,3,0,1] row_mask:0xf bank_mask:0xf bound_ctrl:1
	s_waitcnt lgkmcnt(3)
	v_pk_mul_f32 v[36:37], v[122:123], v[130:131] op_sel_hi:[1,0]
	v_pk_mul_f32 v[38:39], v[124:125], v[130:131] op_sel_hi:[1,0]
	v_add_f32_dpp v34, v34, v34 row_ror:4 row_mask:0xf bank_mask:0xf bound_ctrl:1
	v_pk_fma_f32 v[36:37], v[28:29], v[118:119], v[36:37]
	v_pk_fma_f32 v[38:39], v[30:31], v[120:121], v[38:39]
	v_add_f32_dpp v34, v34, v34 row_ror:8 row_mask:0xf bank_mask:0xf bound_ctrl:1
	ds_read_b128 v[142:145], v94 offset:7312
	ds_read_b128 v[146:149], v94 offset:7568
	v_pk_fma_f32 v[28:29], v[114:115], v[34:35], v[36:37] op_sel_hi:[1,0,1] neg_lo:[0,1,0] neg_hi:[0,1,0]
	v_pk_fma_f32 v[30:31], v[116:117], v[34:35], v[38:39] op_sel_hi:[1,0,1] neg_lo:[0,1,0] neg_hi:[0,1,0]
	v_cndmask_b32_e64 v42, v42, v34, s[82:83]
	ds_read_b32 v154, v95 offset:8080
	s_waitcnt lgkmcnt(4)
	v_pk_mul_f32 v[24:25], v[30:31], v[136:137]
	v_pk_mul_f32 v[26:27], v[30:31], v[152:153]
	v_pk_fma_f32 v[24:25], v[28:29], v[134:135], v[24:25]
	v_pk_fma_f32 v[26:27], v[28:29], v[150:151], v[26:27]
	v_add_f32_e32 v34, v24, v25
	ds_read_b128 v[110:113], v94 offset:8160
	v_add_f32_e32 v55, v26, v27
	v_add_f32_dpp v34, v34, v34 quad_perm:[1,0,3,2] row_mask:0xf bank_mask:0xf bound_ctrl:1
	ds_read_b128 v[126:129], v94 offset:9184
	ds_read_b128 v[114:117], v94 offset:8416
	v_add_f32_dpp v34, v34, v34 quad_perm:[2,3,0,1] row_mask:0xf bank_mask:0xf bound_ctrl:1
	s_waitcnt lgkmcnt(3)
	v_pk_mul_f32 v[36:37], v[146:147], v[154:155] op_sel_hi:[1,0]
	v_pk_mul_f32 v[38:39], v[148:149], v[154:155] op_sel_hi:[1,0]
	v_add_f32_dpp v34, v34, v34 row_ror:4 row_mask:0xf bank_mask:0xf bound_ctrl:1
	v_pk_fma_f32 v[36:37], v[28:29], v[142:143], v[36:37]
	v_pk_fma_f32 v[38:39], v[30:31], v[144:145], v[38:39]
	v_add_f32_dpp v34, v34, v34 row_ror:8 row_mask:0xf bank_mask:0xf bound_ctrl:1
	ds_read_b128 v[118:121], v94 offset:8672
	ds_read_b128 v[122:125], v94 offset:8928
	v_pk_fma_f32 v[28:29], v[138:139], v[34:35], v[36:37] op_sel_hi:[1,0,1] neg_lo:[0,1,0] neg_hi:[0,1,0]
	v_pk_fma_f32 v[30:31], v[140:141], v[34:35], v[38:39] op_sel_hi:[1,0,1] neg_lo:[0,1,0] neg_hi:[0,1,0]
	v_cndmask_b32_e64 v42, v42, v34, s[48:49]
	ds_read_b32 v130, v95 offset:9440
	s_waitcnt lgkmcnt(4)
	v_pk_mul_f32 v[24:25], v[30:31], v[112:113]
	v_pk_mul_f32 v[26:27], v[30:31], v[128:129]
	v_pk_fma_f32 v[24:25], v[28:29], v[110:111], v[24:25]
	v_pk_fma_f32 v[26:27], v[28:29], v[126:127], v[26:27]
	v_add_f32_e32 v34, v24, v25
	ds_read_b128 v[134:137], v94 offset:9520
	v_add_f32_e32 v56, v26, v27
	v_add_f32_dpp v34, v34, v34 quad_perm:[1,0,3,2] row_mask:0xf bank_mask:0xf bound_ctrl:1
	ds_read_b128 v[150:153], v94 offset:10544
	ds_read_b128 v[138:141], v94 offset:9776
	v_add_f32_dpp v34, v34, v34 quad_perm:[2,3,0,1] row_mask:0xf bank_mask:0xf bound_ctrl:1
	s_waitcnt lgkmcnt(3)
	v_pk_mul_f32 v[36:37], v[122:123], v[130:131] op_sel_hi:[1,0]
	v_pk_mul_f32 v[38:39], v[124:125], v[130:131] op_sel_hi:[1,0]
	v_add_f32_dpp v34, v34, v34 row_ror:4 row_mask:0xf bank_mask:0xf bound_ctrl:1
	v_pk_fma_f32 v[36:37], v[28:29], v[118:119], v[36:37]
	v_pk_fma_f32 v[38:39], v[30:31], v[120:121], v[38:39]
	v_add_f32_dpp v34, v34, v34 row_ror:8 row_mask:0xf bank_mask:0xf bound_ctrl:1
	ds_read_b128 v[142:145], v94 offset:10032
	ds_read_b128 v[146:149], v94 offset:10288
	v_pk_fma_f32 v[28:29], v[114:115], v[34:35], v[36:37] op_sel_hi:[1,0,1] neg_lo:[0,1,0] neg_hi:[0,1,0]
	v_pk_fma_f32 v[30:31], v[116:117], v[34:35], v[38:39] op_sel_hi:[1,0,1] neg_lo:[0,1,0] neg_hi:[0,1,0]
	v_cndmask_b32_e64 v42, v42, v34, s[38:39]
	ds_read_b32 v154, v95 offset:10800
	s_waitcnt lgkmcnt(4)
	v_pk_mul_f32 v[24:25], v[30:31], v[136:137]
	v_pk_mul_f32 v[26:27], v[30:31], v[152:153]
	v_pk_fma_f32 v[24:25], v[28:29], v[134:135], v[24:25]
	v_pk_fma_f32 v[26:27], v[28:29], v[150:151], v[26:27]
	v_add_f32_e32 v34, v24, v25
	ds_read_b128 v[110:113], v94 offset:10880
	v_add_f32_e32 v57, v26, v27
	v_add_f32_dpp v34, v34, v34 quad_perm:[1,0,3,2] row_mask:0xf bank_mask:0xf bound_ctrl:1
	ds_read_b128 v[126:129], v94 offset:11904
	ds_read_b128 v[114:117], v94 offset:11136
	v_add_f32_dpp v34, v34, v34 quad_perm:[2,3,0,1] row_mask:0xf bank_mask:0xf bound_ctrl:1
	s_waitcnt lgkmcnt(3)
	v_pk_mul_f32 v[36:37], v[146:147], v[154:155] op_sel_hi:[1,0]
	v_pk_mul_f32 v[38:39], v[148:149], v[154:155] op_sel_hi:[1,0]
	v_add_f32_dpp v34, v34, v34 row_ror:4 row_mask:0xf bank_mask:0xf bound_ctrl:1
	v_pk_fma_f32 v[36:37], v[28:29], v[142:143], v[36:37]
	v_pk_fma_f32 v[38:39], v[30:31], v[144:145], v[38:39]
	v_add_f32_dpp v34, v34, v34 row_ror:8 row_mask:0xf bank_mask:0xf bound_ctrl:1
	ds_read_b128 v[118:121], v94 offset:11392
	ds_read_b128 v[122:125], v94 offset:11648
	v_pk_fma_f32 v[28:29], v[138:139], v[34:35], v[36:37] op_sel_hi:[1,0,1] neg_lo:[0,1,0] neg_hi:[0,1,0]
	v_pk_fma_f32 v[30:31], v[140:141], v[34:35], v[38:39] op_sel_hi:[1,0,1] neg_lo:[0,1,0] neg_hi:[0,1,0]
	v_cndmask_b32_e64 v42, v42, v34, s[42:43]
	ds_read_b32 v130, v95 offset:12160
	s_waitcnt lgkmcnt(4)
	v_pk_mul_f32 v[24:25], v[30:31], v[112:113]
	v_pk_mul_f32 v[26:27], v[30:31], v[128:129]
	v_pk_fma_f32 v[24:25], v[28:29], v[110:111], v[24:25]
	v_pk_fma_f32 v[26:27], v[28:29], v[126:127], v[26:27]
	v_add_f32_e32 v34, v24, v25
	ds_read_b128 v[134:137], v94 offset:12240
	v_add_f32_e32 v58, v26, v27
	v_add_f32_dpp v34, v34, v34 quad_perm:[1,0,3,2] row_mask:0xf bank_mask:0xf bound_ctrl:1
	ds_read_b128 v[150:153], v94 offset:13264
	ds_read_b128 v[138:141], v94 offset:12496
	v_add_f32_dpp v34, v34, v34 quad_perm:[2,3,0,1] row_mask:0xf bank_mask:0xf bound_ctrl:1
	s_waitcnt lgkmcnt(3)
	v_pk_mul_f32 v[36:37], v[122:123], v[130:131] op_sel_hi:[1,0]
	v_pk_mul_f32 v[38:39], v[124:125], v[130:131] op_sel_hi:[1,0]
	v_add_f32_dpp v34, v34, v34 row_ror:4 row_mask:0xf bank_mask:0xf bound_ctrl:1
	v_pk_fma_f32 v[36:37], v[28:29], v[118:119], v[36:37]
	v_pk_fma_f32 v[38:39], v[30:31], v[120:121], v[38:39]
	v_add_f32_dpp v34, v34, v34 row_ror:8 row_mask:0xf bank_mask:0xf bound_ctrl:1
	ds_read_b128 v[142:145], v94 offset:12752
	ds_read_b128 v[146:149], v94 offset:13008
	v_pk_fma_f32 v[28:29], v[114:115], v[34:35], v[36:37] op_sel_hi:[1,0,1] neg_lo:[0,1,0] neg_hi:[0,1,0]
	v_pk_fma_f32 v[30:31], v[116:117], v[34:35], v[38:39] op_sel_hi:[1,0,1] neg_lo:[0,1,0] neg_hi:[0,1,0]
	v_cndmask_b32_e64 v42, v42, v34, s[44:45]
	ds_read_b32 v154, v95 offset:13520
	s_waitcnt lgkmcnt(4)
	v_pk_mul_f32 v[24:25], v[30:31], v[136:137]
	v_pk_mul_f32 v[26:27], v[30:31], v[152:153]
	v_pk_fma_f32 v[24:25], v[28:29], v[134:135], v[24:25]
	v_pk_fma_f32 v[26:27], v[28:29], v[150:151], v[26:27]
	v_add_f32_e32 v34, v24, v25
	ds_read_b128 v[110:113], v94 offset:13600
	v_add_f32_e32 v59, v26, v27
	v_add_f32_dpp v34, v34, v34 quad_perm:[1,0,3,2] row_mask:0xf bank_mask:0xf bound_ctrl:1
	ds_read_b128 v[126:129], v94 offset:14624
	ds_read_b128 v[114:117], v94 offset:13856
	v_add_f32_dpp v34, v34, v34 quad_perm:[2,3,0,1] row_mask:0xf bank_mask:0xf bound_ctrl:1
	s_waitcnt lgkmcnt(3)
	v_pk_mul_f32 v[36:37], v[146:147], v[154:155] op_sel_hi:[1,0]
	v_pk_mul_f32 v[38:39], v[148:149], v[154:155] op_sel_hi:[1,0]
	v_add_f32_dpp v34, v34, v34 row_ror:4 row_mask:0xf bank_mask:0xf bound_ctrl:1
	v_pk_fma_f32 v[36:37], v[28:29], v[142:143], v[36:37]
	v_pk_fma_f32 v[38:39], v[30:31], v[144:145], v[38:39]
	v_add_f32_dpp v34, v34, v34 row_ror:8 row_mask:0xf bank_mask:0xf bound_ctrl:1
	ds_read_b128 v[118:121], v94 offset:14112
	ds_read_b128 v[122:125], v94 offset:14368
	v_pk_fma_f32 v[28:29], v[138:139], v[34:35], v[36:37] op_sel_hi:[1,0,1] neg_lo:[0,1,0] neg_hi:[0,1,0]
	v_pk_fma_f32 v[30:31], v[140:141], v[34:35], v[38:39] op_sel_hi:[1,0,1] neg_lo:[0,1,0] neg_hi:[0,1,0]
	v_cndmask_b32_e32 v42, v42, v34, vcc
	ds_read_b32 v130, v95 offset:14880
	s_waitcnt lgkmcnt(4)
	v_pk_mul_f32 v[24:25], v[30:31], v[112:113]
	v_pk_mul_f32 v[26:27], v[30:31], v[128:129]
	v_pk_fma_f32 v[24:25], v[28:29], v[110:111], v[24:25]
	v_pk_fma_f32 v[26:27], v[28:29], v[126:127], v[26:27]
	v_add_f32_e32 v34, v24, v25
	ds_read_b128 v[134:137], v94 offset:14960
	v_add_f32_e32 v60, v26, v27
	v_add_f32_dpp v34, v34, v34 quad_perm:[1,0,3,2] row_mask:0xf bank_mask:0xf bound_ctrl:1
	ds_read_b128 v[150:153], v94 offset:15984
	ds_read_b128 v[138:141], v94 offset:15216
	v_add_f32_dpp v34, v34, v34 quad_perm:[2,3,0,1] row_mask:0xf bank_mask:0xf bound_ctrl:1
	s_waitcnt lgkmcnt(3)
	v_pk_mul_f32 v[36:37], v[122:123], v[130:131] op_sel_hi:[1,0]
	v_pk_mul_f32 v[38:39], v[124:125], v[130:131] op_sel_hi:[1,0]
	v_add_f32_dpp v34, v34, v34 row_ror:4 row_mask:0xf bank_mask:0xf bound_ctrl:1
	v_pk_fma_f32 v[36:37], v[28:29], v[118:119], v[36:37]
	v_pk_fma_f32 v[38:39], v[30:31], v[120:121], v[38:39]
	v_add_f32_dpp v34, v34, v34 row_ror:8 row_mask:0xf bank_mask:0xf bound_ctrl:1
	ds_read_b128 v[142:145], v94 offset:15472
	ds_read_b128 v[146:149], v94 offset:15728
	v_pk_fma_f32 v[28:29], v[114:115], v[34:35], v[36:37] op_sel_hi:[1,0,1] neg_lo:[0,1,0] neg_hi:[0,1,0]
	v_pk_fma_f32 v[30:31], v[116:117], v[34:35], v[38:39] op_sel_hi:[1,0,1] neg_lo:[0,1,0] neg_hi:[0,1,0]
	v_cndmask_b32_e64 v42, v42, v34, s[58:59]
	ds_read_b32 v154, v95 offset:16240
	s_waitcnt lgkmcnt(4)
	v_pk_mul_f32 v[24:25], v[30:31], v[136:137]
	v_pk_mul_f32 v[26:27], v[30:31], v[152:153]
	v_pk_fma_f32 v[24:25], v[28:29], v[134:135], v[24:25]
	v_pk_fma_f32 v[26:27], v[28:29], v[150:151], v[26:27]
	v_add_f32_e32 v34, v24, v25
	ds_read_b128 v[110:113], v94 offset:16320
	v_add_f32_e32 v61, v26, v27
	v_add_f32_dpp v34, v34, v34 quad_perm:[1,0,3,2] row_mask:0xf bank_mask:0xf bound_ctrl:1
	ds_read_b128 v[126:129], v94 offset:17344
	ds_read_b128 v[114:117], v94 offset:16576
	v_add_f32_dpp v34, v34, v34 quad_perm:[2,3,0,1] row_mask:0xf bank_mask:0xf bound_ctrl:1
	s_waitcnt lgkmcnt(3)
	v_pk_mul_f32 v[36:37], v[146:147], v[154:155] op_sel_hi:[1,0]
	v_pk_mul_f32 v[38:39], v[148:149], v[154:155] op_sel_hi:[1,0]
	v_add_f32_dpp v34, v34, v34 row_ror:4 row_mask:0xf bank_mask:0xf bound_ctrl:1
	v_pk_fma_f32 v[36:37], v[28:29], v[142:143], v[36:37]
	v_pk_fma_f32 v[38:39], v[30:31], v[144:145], v[38:39]
	v_add_f32_dpp v34, v34, v34 row_ror:8 row_mask:0xf bank_mask:0xf bound_ctrl:1
	ds_read_b128 v[118:121], v94 offset:16832
	ds_read_b128 v[122:125], v94 offset:17088
	v_pk_fma_f32 v[28:29], v[138:139], v[34:35], v[36:37] op_sel_hi:[1,0,1] neg_lo:[0,1,0] neg_hi:[0,1,0]
	v_pk_fma_f32 v[30:31], v[140:141], v[34:35], v[38:39] op_sel_hi:[1,0,1] neg_lo:[0,1,0] neg_hi:[0,1,0]
	v_cndmask_b32_e64 v42, v42, v34, s[60:61]
	ds_read_b32 v130, v95 offset:17600
	s_waitcnt lgkmcnt(4)
	v_pk_mul_f32 v[24:25], v[30:31], v[112:113]
	v_pk_mul_f32 v[26:27], v[30:31], v[128:129]
	v_pk_fma_f32 v[24:25], v[28:29], v[110:111], v[24:25]
	v_pk_fma_f32 v[26:27], v[28:29], v[126:127], v[26:27]
	v_add_f32_e32 v34, v24, v25
	ds_read_b128 v[134:137], v94 offset:17680
	v_add_f32_e32 v62, v26, v27
	v_add_f32_dpp v34, v34, v34 quad_perm:[1,0,3,2] row_mask:0xf bank_mask:0xf bound_ctrl:1
	ds_read_b128 v[150:153], v94 offset:18704
	ds_read_b128 v[138:141], v94 offset:17936
	v_add_f32_dpp v34, v34, v34 quad_perm:[2,3,0,1] row_mask:0xf bank_mask:0xf bound_ctrl:1
	s_waitcnt lgkmcnt(3)
	v_pk_mul_f32 v[36:37], v[122:123], v[130:131] op_sel_hi:[1,0]
	v_pk_mul_f32 v[38:39], v[124:125], v[130:131] op_sel_hi:[1,0]
	v_add_f32_dpp v34, v34, v34 row_ror:4 row_mask:0xf bank_mask:0xf bound_ctrl:1
	v_pk_fma_f32 v[36:37], v[28:29], v[118:119], v[36:37]
	v_pk_fma_f32 v[38:39], v[30:31], v[120:121], v[38:39]
	v_add_f32_dpp v34, v34, v34 row_ror:8 row_mask:0xf bank_mask:0xf bound_ctrl:1
	ds_read_b128 v[142:145], v94 offset:18192
	ds_read_b128 v[146:149], v94 offset:18448
	v_pk_fma_f32 v[28:29], v[114:115], v[34:35], v[36:37] op_sel_hi:[1,0,1] neg_lo:[0,1,0] neg_hi:[0,1,0]
	v_pk_fma_f32 v[30:31], v[116:117], v[34:35], v[38:39] op_sel_hi:[1,0,1] neg_lo:[0,1,0] neg_hi:[0,1,0]
	v_cndmask_b32_e64 v42, v42, v34, s[62:63]
	ds_read_b32 v154, v95 offset:18960
	s_waitcnt lgkmcnt(4)
	v_pk_mul_f32 v[24:25], v[30:31], v[136:137]
	v_pk_mul_f32 v[26:27], v[30:31], v[152:153]
	v_pk_fma_f32 v[24:25], v[28:29], v[134:135], v[24:25]
	v_pk_fma_f32 v[26:27], v[28:29], v[150:151], v[26:27]
	v_add_f32_e32 v34, v24, v25
	ds_read_b128 v[110:113], v94 offset:19040
	v_add_f32_e32 v63, v26, v27
	v_add_f32_dpp v34, v34, v34 quad_perm:[1,0,3,2] row_mask:0xf bank_mask:0xf bound_ctrl:1
	ds_read_b128 v[126:129], v94 offset:20064
	ds_read_b128 v[114:117], v94 offset:19296
	v_add_f32_dpp v34, v34, v34 quad_perm:[2,3,0,1] row_mask:0xf bank_mask:0xf bound_ctrl:1
	s_waitcnt lgkmcnt(3)
	v_pk_mul_f32 v[36:37], v[146:147], v[154:155] op_sel_hi:[1,0]
	v_pk_mul_f32 v[38:39], v[148:149], v[154:155] op_sel_hi:[1,0]
	v_add_f32_dpp v34, v34, v34 row_ror:4 row_mask:0xf bank_mask:0xf bound_ctrl:1
	v_pk_fma_f32 v[36:37], v[28:29], v[142:143], v[36:37]
	v_pk_fma_f32 v[38:39], v[30:31], v[144:145], v[38:39]
	v_add_f32_dpp v34, v34, v34 row_ror:8 row_mask:0xf bank_mask:0xf bound_ctrl:1
	ds_read_b128 v[118:121], v94 offset:19552
	ds_read_b128 v[122:125], v94 offset:19808
	v_pk_fma_f32 v[28:29], v[138:139], v[34:35], v[36:37] op_sel_hi:[1,0,1] neg_lo:[0,1,0] neg_hi:[0,1,0]
	v_pk_fma_f32 v[30:31], v[140:141], v[34:35], v[38:39] op_sel_hi:[1,0,1] neg_lo:[0,1,0] neg_hi:[0,1,0]
	v_cndmask_b32_e64 v42, v42, v34, s[66:67]
	ds_read_b32 v130, v95 offset:20320
	s_waitcnt lgkmcnt(4)
	v_pk_mul_f32 v[24:25], v[30:31], v[112:113]
	v_pk_mul_f32 v[26:27], v[30:31], v[128:129]
	v_pk_fma_f32 v[24:25], v[28:29], v[110:111], v[24:25]
	v_pk_fma_f32 v[26:27], v[28:29], v[126:127], v[26:27]
	v_add_f32_e32 v34, v24, v25
	ds_read_b128 v[134:137], v94 offset:20400
	v_add_f32_e32 v64, v26, v27
	v_add_f32_dpp v34, v34, v34 quad_perm:[1,0,3,2] row_mask:0xf bank_mask:0xf bound_ctrl:1
	ds_read_b128 v[150:153], v94 offset:21424
	ds_read_b128 v[138:141], v94 offset:20656
	v_add_f32_dpp v34, v34, v34 quad_perm:[2,3,0,1] row_mask:0xf bank_mask:0xf bound_ctrl:1
	s_waitcnt lgkmcnt(3)
	v_pk_mul_f32 v[36:37], v[122:123], v[130:131] op_sel_hi:[1,0]
	v_pk_mul_f32 v[38:39], v[124:125], v[130:131] op_sel_hi:[1,0]
	v_add_f32_dpp v34, v34, v34 row_ror:4 row_mask:0xf bank_mask:0xf bound_ctrl:1
	v_pk_fma_f32 v[36:37], v[28:29], v[118:119], v[36:37]
	v_pk_fma_f32 v[38:39], v[30:31], v[120:121], v[38:39]
	v_add_f32_dpp v34, v34, v34 row_ror:8 row_mask:0xf bank_mask:0xf bound_ctrl:1
	ds_read_b128 v[142:145], v94 offset:20912
	ds_read_b128 v[146:149], v94 offset:21168
	v_pk_fma_f32 v[28:29], v[114:115], v[34:35], v[36:37] op_sel_hi:[1,0,1] neg_lo:[0,1,0] neg_hi:[0,1,0]
	v_pk_fma_f32 v[30:31], v[116:117], v[34:35], v[38:39] op_sel_hi:[1,0,1] neg_lo:[0,1,0] neg_hi:[0,1,0]
	v_cndmask_b32_e64 v42, v42, v34, s[64:65]
	ds_read_b32 v154, v95 offset:21680
	s_waitcnt lgkmcnt(4)
	v_pk_mul_f32 v[24:25], v[30:31], v[136:137]
	v_pk_mul_f32 v[26:27], v[30:31], v[152:153]
	v_pk_fma_f32 v[24:25], v[28:29], v[134:135], v[24:25]
	v_pk_fma_f32 v[26:27], v[28:29], v[150:151], v[26:27]
	v_add_f32_e32 v34, v24, v25
	v_lshl_add_u64 v[70:71], v[70:71], 0, s[2:3]
	v_add_f32_e32 v65, v26, v27
	v_add_f32_dpp v34, v34, v34 quad_perm:[1,0,3,2] row_mask:0xf bank_mask:0xf bound_ctrl:1
	v_lshl_add_u64 v[72:73], v[72:73], 0, s[20:21]
	v_lshl_add_u64 v[74:75], v[74:75], 0, s[20:21]
	v_add_f32_dpp v34, v34, v34 quad_perm:[2,3,0,1] row_mask:0xf bank_mask:0xf bound_ctrl:1
	s_waitcnt lgkmcnt(0)
	v_pk_mul_f32 v[36:37], v[146:147], v[154:155] op_sel_hi:[1,0]
	v_pk_mul_f32 v[38:39], v[148:149], v[154:155] op_sel_hi:[1,0]
	v_add_f32_dpp v34, v34, v34 row_ror:4 row_mask:0xf bank_mask:0xf bound_ctrl:1
	v_pk_fma_f32 v[36:37], v[28:29], v[142:143], v[36:37]
	v_pk_fma_f32 v[38:39], v[30:31], v[144:145], v[38:39]
	v_add_f32_dpp v34, v34, v34 row_ror:8 row_mask:0xf bank_mask:0xf bound_ctrl:1
	v_pk_fma_f32 v[28:29], v[138:139], v[34:35], v[36:37] op_sel_hi:[1,0,1] neg_lo:[0,1,0] neg_hi:[0,1,0]
	v_pk_fma_f32 v[30:31], v[140:141], v[34:35], v[38:39] op_sel_hi:[1,0,1] neg_lo:[0,1,0] neg_hi:[0,1,0]
	v_cndmask_b32_e64 v42, v42, v34, s[68:69]
	v_add_f32_dpp v50, v50, v50 row_ror:8 row_mask:0xf bank_mask:0xf bound_ctrl:1
	v_add_f32_dpp v51, v51, v51 row_ror:8 row_mask:0xf bank_mask:0xf bound_ctrl:1
	v_add_f32_dpp v52, v52, v52 row_ror:8 row_mask:0xf bank_mask:0xf bound_ctrl:1
	v_add_f32_dpp v53, v53, v53 row_ror:8 row_mask:0xf bank_mask:0xf bound_ctrl:1
	v_add_f32_dpp v54, v54, v54 row_ror:8 row_mask:0xf bank_mask:0xf bound_ctrl:1
	v_add_f32_dpp v55, v55, v55 row_ror:8 row_mask:0xf bank_mask:0xf bound_ctrl:1
	v_add_f32_dpp v56, v56, v56 row_ror:8 row_mask:0xf bank_mask:0xf bound_ctrl:1
	v_add_f32_dpp v57, v57, v57 row_ror:8 row_mask:0xf bank_mask:0xf bound_ctrl:1
	v_add_f32_dpp v50, v58, v58 row_ror:8 row_mask:0xf bank_mask:0xc bound_ctrl:1
	v_add_f32_dpp v51, v59, v59 row_ror:8 row_mask:0xf bank_mask:0xc bound_ctrl:1
	v_add_f32_dpp v52, v60, v60 row_ror:8 row_mask:0xf bank_mask:0xc bound_ctrl:1
	v_add_f32_dpp v53, v61, v61 row_ror:8 row_mask:0xf bank_mask:0xc bound_ctrl:1
	v_add_f32_dpp v54, v62, v62 row_ror:8 row_mask:0xf bank_mask:0xc bound_ctrl:1
	v_add_f32_dpp v55, v63, v63 row_ror:8 row_mask:0xf bank_mask:0xc bound_ctrl:1
	v_add_f32_dpp v56, v64, v64 row_ror:8 row_mask:0xf bank_mask:0xc bound_ctrl:1
	v_add_f32_dpp v57, v65, v65 row_ror:8 row_mask:0xf bank_mask:0xc bound_ctrl:1
	s_mov_b32 s2, 0xcccccccc
	s_mov_b32 s3, 0xcccccccc
	v_add_f32_dpp v50, v50, v50 row_half_mirror row_mask:0xf bank_mask:0x5 bound_ctrl:1
	v_add_f32_dpp v51, v51, v51 row_half_mirror row_mask:0xf bank_mask:0x5 bound_ctrl:1
	v_add_f32_dpp v52, v52, v52 row_half_mirror row_mask:0xf bank_mask:0x5 bound_ctrl:1
	v_add_f32_dpp v53, v53, v53 row_half_mirror row_mask:0xf bank_mask:0x5 bound_ctrl:1
	s_mov_b32 s20, 0xaaaaaaaa
	s_mov_b32 s21, 0xaaaaaaaa
	v_add_f32_dpp v50, v54, v54 row_half_mirror row_mask:0xf bank_mask:0xa bound_ctrl:1
	v_add_f32_dpp v51, v55, v55 row_half_mirror row_mask:0xf bank_mask:0xa bound_ctrl:1
	v_add_f32_dpp v52, v56, v56 row_half_mirror row_mask:0xf bank_mask:0xa bound_ctrl:1
	v_add_f32_dpp v53, v57, v57 row_half_mirror row_mask:0xf bank_mask:0xa bound_ctrl:1
	v_cndmask_b32_e64 v58, v52, v50, s[2:3]
	v_cndmask_b32_e64 v59, v53, v51, s[2:3]
	v_cndmask_b32_e64 v60, v50, v52, s[2:3]
	v_cndmask_b32_e64 v61, v51, v53, s[2:3]
	v_add_f32_dpp v50, v58, v60 quad_perm:[2,3,0,1] row_mask:0xf bank_mask:0xf bound_ctrl:1
	v_add_f32_dpp v51, v59, v61 quad_perm:[2,3,0,1] row_mask:0xf bank_mask:0xf bound_ctrl:1
	v_lshl_add_u64 v[24:25], v[68:69], 0, s[0:1]
	s_add_u32 s0, s0, 0x1000
	s_addc_u32 s1, s1, 0
	v_cndmask_b32_e64 v58, v51, v50, s[20:21]
	v_cndmask_b32_e64 v60, v50, v51, s[20:21]
	s_add_i32 s24, s24, 1
	s_cmp_lg_u32 s0, 0xac000
	v_add_f32_dpp v43, v58, v60 quad_perm:[1,0,3,2] row_mask:0xf bank_mask:0xf bound_ctrl:1
	v_fma_f32 v40, -v44, v42, v43
	v_fmac_f32_e32 v40, v48, v45
	global_store_dword v[24:25], v40, off
	s_barrier
	s_cbranch_scc0 .LBB0_81

.LBB0_151:
	s_bitcmp1_b32 s24, 0
	s_cselect_b32 s2, 0x5500, 0
	v_lshl_or_b32 v94, v93, 2, s2
	v_lshl_add_u32 v95, v0, 2, s2
	v_mov_b32_e32 v96, s2
	v_mul_u32_u24_e32 v46, 0x154, v93
	v_add_u32_e32 v47, v46, v96
	v_add_u32_e32 v46, v46, v95
	ds_read_b64 v[44:45], v47 offset:1344
	ds_read_b32 v48, v46 offset:1280
	ds_read_b128 v[110:113], v94
	ds_read_b128 v[126:129], v94 offset:1024
	ds_read_b128 v[114:117], v94 offset:256
	ds_read_b128 v[118:121], v94 offset:512
	ds_read_b128 v[122:125], v94 offset:768
	ds_read_b32 v130, v95 offset:1280
	s_mov_b64 s[2:3], 0x100
	s_mov_b64 s[20:21], 0x800
	s_waitcnt lgkmcnt(4)
	v_pk_mul_f32 v[24:25], v[30:31], v[112:113]
	v_pk_mul_f32 v[26:27], v[30:31], v[128:129]
	v_pk_fma_f32 v[24:25], v[28:29], v[110:111], v[24:25]
	v_pk_fma_f32 v[26:27], v[28:29], v[126:127], v[26:27]
	v_add_f32_e32 v34, v24, v25
	ds_read_b128 v[134:137], v94 offset:1360
	v_add_f32_e32 v50, v26, v27
	v_add_f32_dpp v34, v34, v34 quad_perm:[1,0,3,2] row_mask:0xf bank_mask:0xf bound_ctrl:1
	ds_read_b128 v[150:153], v94 offset:2384
	ds_read_b128 v[138:141], v94 offset:1616
	v_add_f32_dpp v34, v34, v34 quad_perm:[2,3,0,1] row_mask:0xf bank_mask:0xf bound_ctrl:1
	s_waitcnt lgkmcnt(3)
	v_pk_mul_f32 v[36:37], v[122:123], v[130:131] op_sel_hi:[1,0]
	v_pk_mul_f32 v[38:39], v[124:125], v[130:131] op_sel_hi:[1,0]
	v_add_f32_dpp v34, v34, v34 row_ror:4 row_mask:0xf bank_mask:0xf bound_ctrl:1
	v_pk_fma_f32 v[36:37], v[28:29], v[118:119], v[36:37]
	v_pk_fma_f32 v[38:39], v[30:31], v[120:121], v[38:39]
	v_add_f32_dpp v34, v34, v34 row_ror:8 row_mask:0xf bank_mask:0xf bound_ctrl:1
	ds_read_b128 v[142:145], v94 offset:1872
	ds_read_b128 v[146:149], v94 offset:2128
	v_pk_fma_f32 v[28:29], v[114:115], v[34:35], v[36:37] op_sel_hi:[1,0,1] neg_lo:[0,1,0] neg_hi:[0,1,0]
	v_pk_fma_f32 v[30:31], v[116:117], v[34:35], v[38:39] op_sel_hi:[1,0,1] neg_lo:[0,1,0] neg_hi:[0,1,0]
	v_cndmask_b32_e64 v42, 0, v34, s[72:73]
	ds_read_b32 v154, v95 offset:2640
	s_waitcnt lgkmcnt(4)
	v_pk_mul_f32 v[24:25], v[30:31], v[136:137]
	v_pk_mul_f32 v[26:27], v[30:31], v[152:153]
	v_pk_fma_f32 v[24:25], v[28:29], v[134:135], v[24:25]
	v_pk_fma_f32 v[26:27], v[28:29], v[150:151], v[26:27]
	v_add_f32_e32 v34, v24, v25
	ds_read_b128 v[110:113], v94 offset:2720
	v_add_f32_e32 v51, v26, v27
	v_add_f32_dpp v34, v34, v34 quad_perm:[1,0,3,2] row_mask:0xf bank_mask:0xf bound_ctrl:1
	ds_read_b128 v[126:129], v94 offset:3744
	ds_read_b128 v[114:117], v94 offset:2976
	v_add_f32_dpp v34, v34, v34 quad_perm:[2,3,0,1] row_mask:0xf bank_mask:0xf bound_ctrl:1
	s_waitcnt lgkmcnt(3)
	v_pk_mul_f32 v[36:37], v[146:147], v[154:155] op_sel_hi:[1,0]
	v_pk_mul_f32 v[38:39], v[148:149], v[154:155] op_sel_hi:[1,0]
	v_add_f32_dpp v34, v34, v34 row_ror:4 row_mask:0xf bank_mask:0xf bound_ctrl:1
	v_pk_fma_f32 v[36:37], v[28:29], v[142:143], v[36:37]
	v_pk_fma_f32 v[38:39], v[30:31], v[144:145], v[38:39]
	v_add_f32_dpp v34, v34, v34 row_ror:8 row_mask:0xf bank_mask:0xf bound_ctrl:1
	ds_read_b128 v[118:121], v94 offset:3232
	ds_read_b128 v[122:125], v94 offset:3488
	v_pk_fma_f32 v[28:29], v[138:139], v[34:35], v[36:37] op_sel_hi:[1,0,1] neg_lo:[0,1,0] neg_hi:[0,1,0]
	v_pk_fma_f32 v[30:31], v[140:141], v[34:35], v[38:39] op_sel_hi:[1,0,1] neg_lo:[0,1,0] neg_hi:[0,1,0]
	v_cndmask_b32_e64 v42, v42, v34, s[30:31]
	ds_read_b32 v130, v95 offset:4000
	s_waitcnt lgkmcnt(4)
	v_pk_mul_f32 v[24:25], v[30:31], v[112:113]
	v_pk_mul_f32 v[26:27], v[30:31], v[128:129]
	v_pk_fma_f32 v[24:25], v[28:29], v[110:111], v[24:25]
	v_pk_fma_f32 v[26:27], v[28:29], v[126:127], v[26:27]
	v_add_f32_e32 v34, v24, v25
	ds_read_b128 v[134:137], v94 offset:4080
	v_add_f32_e32 v52, v26, v27
	v_add_f32_dpp v34, v34, v34 quad_perm:[1,0,3,2] row_mask:0xf bank_mask:0xf bound_ctrl:1
	ds_read_b128 v[150:153], v94 offset:5104
	ds_read_b128 v[138:141], v94 offset:4336
	v_add_f32_dpp v34, v34, v34 quad_perm:[2,3,0,1] row_mask:0xf bank_mask:0xf bound_ctrl:1
	s_waitcnt lgkmcnt(3)
	v_pk_mul_f32 v[36:37], v[122:123], v[130:131] op_sel_hi:[1,0]
	v_pk_mul_f32 v[38:39], v[124:125], v[130:131] op_sel_hi:[1,0]
	v_add_f32_dpp v34, v34, v34 row_ror:4 row_mask:0xf bank_mask:0xf bound_ctrl:1
	v_pk_fma_f32 v[36:37], v[28:29], v[118:119], v[36:37]
	v_pk_fma_f32 v[38:39], v[30:31], v[120:121], v[38:39]
	v_add_f32_dpp v34, v34, v34 row_ror:8 row_mask:0xf bank_mask:0xf bound_ctrl:1
	ds_read_b128 v[142:145], v94 offset:4592
	ds_read_b128 v[146:149], v94 offset:4848
	v_pk_fma_f32 v[28:29], v[114:115], v[34:35], v[36:37] op_sel_hi:[1,0,1] neg_lo:[0,1,0] neg_hi:[0,1,0]
	v_pk_fma_f32 v[30:31], v[116:117], v[34:35], v[38:39] op_sel_hi:[1,0,1] neg_lo:[0,1,0] neg_hi:[0,1,0]
	v_cndmask_b32_e64 v42, v42, v34, s[70:71]
	ds_read_b32 v154, v95 offset:5360
	s_waitcnt lgkmcnt(4)
	v_pk_mul_f32 v[24:25], v[30:31], v[136:137]
	v_pk_mul_f32 v[26:27], v[30:31], v[152:153]
	v_pk_fma_f32 v[24:25], v[28:29], v[134:135], v[24:25]
	v_pk_fma_f32 v[26:27], v[28:29], v[150:151], v[26:27]
	v_add_f32_e32 v34, v24, v25
	ds_read_b128 v[110:113], v94 offset:5440
	v_add_f32_e32 v53, v26, v27
	v_add_f32_dpp v34, v34, v34 quad_perm:[1,0,3,2] row_mask:0xf bank_mask:0xf bound_ctrl:1
	ds_read_b128 v[126:129], v94 offset:6464
	ds_read_b128 v[114:117], v94 offset:5696
	v_add_f32_dpp v34, v34, v34 quad_perm:[2,3,0,1] row_mask:0xf bank_mask:0xf bound_ctrl:1
	s_waitcnt lgkmcnt(3)
	v_pk_mul_f32 v[36:37], v[146:147], v[154:155] op_sel_hi:[1,0]
	v_pk_mul_f32 v[38:39], v[148:149], v[154:155] op_sel_hi:[1,0]
	v_add_f32_dpp v34, v34, v34 row_ror:4 row_mask:0xf bank_mask:0xf bound_ctrl:1
	v_pk_fma_f32 v[36:37], v[28:29], v[142:143], v[36:37]
	v_pk_fma_f32 v[38:39], v[30:31], v[144:145], v[38:39]
	v_add_f32_dpp v34, v34, v34 row_ror:8 row_mask:0xf bank_mask:0xf bound_ctrl:1
	ds_read_b128 v[118:121], v94 offset:5952
	ds_read_b128 v[122:125], v94 offset:6208
	v_pk_fma_f32 v[28:29], v[138:139], v[34:35], v[36:37] op_sel_hi:[1,0,1] neg_lo:[0,1,0] neg_hi:[0,1,0]
	v_pk_fma_f32 v[30:31], v[140:141], v[34:35], v[38:39] op_sel_hi:[1,0,1] neg_lo:[0,1,0] neg_hi:[0,1,0]
	v_cndmask_b32_e64 v42, v42, v34, s[40:41]
	ds_read_b32 v130, v95 offset:6720
	s_waitcnt lgkmcnt(4)
	v_pk_mul_f32 v[24:25], v[30:31], v[112:113]
	v_pk_mul_f32 v[26:27], v[30:31], v[128:129]
	v_pk_fma_f32 v[24:25], v[28:29], v[110:111], v[24:25]
	v_pk_fma_f32 v[26:27], v[28:29], v[126:127], v[26:27]
	v_add_f32_e32 v34, v24, v25
	ds_read_b128 v[134:137], v94 offset:6800
	v_add_f32_e32 v54, v26, v27
	v_add_f32_dpp v34, v34, v34 quad_perm:[1,0,3,2] row_mask:0xf bank_mask:0xf bound_ctrl:1
	ds_read_b128 v[150:153], v94 offset:7824
	ds_read_b128 v[138:141], v94 offset:7056
	v_add_f32_dpp v34, v34, v34 quad_perm:[2,3,0,1] row_mask:0xf bank_mask:0xf bound_ctrl:1
	s_waitcnt lgkmcnt(3)
	v_pk_mul_f32 v[36:37], v[122:123], v[130:131] op_sel_hi:[1,0]
	v_pk_mul_f32 v[38:39], v[124:125], v[130:131] op_sel_hi:[1,0]
	v_add_f32_dpp v34, v34, v34 row_ror:4 row_mask:0xf bank_mask:0xf bound_ctrl:1
	v_pk_fma_f32 v[36:37], v[28:29], v[118:119], v[36:37]
	v_pk_fma_f32 v[38:39], v[30:31], v[120:121], v[38:39]
	v_add_f32_dpp v34, v34, v34 row_ror:8 row_mask:0xf bank_mask:0xf bound_ctrl:1
	ds_read_b128 v[142:145], v94 offset:7312
	ds_read_b128 v[146:149], v94 offset:7568
	v_pk_fma_f32 v[28:29], v[114:115], v[34:35], v[36:37] op_sel_hi:[1,0,1] neg_lo:[0,1,0] neg_hi:[0,1,0]
	v_pk_fma_f32 v[30:31], v[116:117], v[34:35], v[38:39] op_sel_hi:[1,0,1] neg_lo:[0,1,0] neg_hi:[0,1,0]
	v_cndmask_b32_e64 v42, v42, v34, s[42:43]
	ds_read_b32 v154, v95 offset:8080
	s_waitcnt lgkmcnt(4)
	v_pk_mul_f32 v[24:25], v[30:31], v[136:137]
	v_pk_mul_f32 v[26:27], v[30:31], v[152:153]
	v_pk_fma_f32 v[24:25], v[28:29], v[134:135], v[24:25]
	v_pk_fma_f32 v[26:27], v[28:29], v[150:151], v[26:27]
	v_add_f32_e32 v34, v24, v25
	ds_read_b128 v[110:113], v94 offset:8160
	v_add_f32_e32 v55, v26, v27
	v_add_f32_dpp v34, v34, v34 quad_perm:[1,0,3,2] row_mask:0xf bank_mask:0xf bound_ctrl:1
	ds_read_b128 v[126:129], v94 offset:9184
	ds_read_b128 v[114:117], v94 offset:8416
	v_add_f32_dpp v34, v34, v34 quad_perm:[2,3,0,1] row_mask:0xf bank_mask:0xf bound_ctrl:1
	s_waitcnt lgkmcnt(3)
	v_pk_mul_f32 v[36:37], v[146:147], v[154:155] op_sel_hi:[1,0]
	v_pk_mul_f32 v[38:39], v[148:149], v[154:155] op_sel_hi:[1,0]
	v_add_f32_dpp v34, v34, v34 row_ror:4 row_mask:0xf bank_mask:0xf bound_ctrl:1
	v_pk_fma_f32 v[36:37], v[28:29], v[142:143], v[36:37]
	v_pk_fma_f32 v[38:39], v[30:31], v[144:145], v[38:39]
	v_add_f32_dpp v34, v34, v34 row_ror:8 row_mask:0xf bank_mask:0xf bound_ctrl:1
	ds_read_b128 v[118:121], v94 offset:8672
	ds_read_b128 v[122:125], v94 offset:8928
	v_pk_fma_f32 v[28:29], v[138:139], v[34:35], v[36:37] op_sel_hi:[1,0,1] neg_lo:[0,1,0] neg_hi:[0,1,0]
	v_pk_fma_f32 v[30:31], v[140:141], v[34:35], v[38:39] op_sel_hi:[1,0,1] neg_lo:[0,1,0] neg_hi:[0,1,0]
	v_cndmask_b32_e64 v42, v42, v34, s[44:45]
	ds_read_b32 v130, v95 offset:9440
	s_waitcnt lgkmcnt(4)
	v_pk_mul_f32 v[24:25], v[30:31], v[112:113]
	v_pk_mul_f32 v[26:27], v[30:31], v[128:129]
	v_pk_fma_f32 v[24:25], v[28:29], v[110:111], v[24:25]
	v_pk_fma_f32 v[26:27], v[28:29], v[126:127], v[26:27]
	v_add_f32_e32 v34, v24, v25
	ds_read_b128 v[134:137], v94 offset:9520
	v_add_f32_e32 v56, v26, v27
	v_add_f32_dpp v34, v34, v34 quad_perm:[1,0,3,2] row_mask:0xf bank_mask:0xf bound_ctrl:1
	ds_read_b128 v[150:153], v94 offset:10544
	ds_read_b128 v[138:141], v94 offset:9776
	v_add_f32_dpp v34, v34, v34 quad_perm:[2,3,0,1] row_mask:0xf bank_mask:0xf bound_ctrl:1
	s_waitcnt lgkmcnt(3)
	v_pk_mul_f32 v[36:37], v[122:123], v[130:131] op_sel_hi:[1,0]
	v_pk_mul_f32 v[38:39], v[124:125], v[130:131] op_sel_hi:[1,0]
	v_add_f32_dpp v34, v34, v34 row_ror:4 row_mask:0xf bank_mask:0xf bound_ctrl:1
	v_pk_fma_f32 v[36:37], v[28:29], v[118:119], v[36:37]
	v_pk_fma_f32 v[38:39], v[30:31], v[120:121], v[38:39]
	v_add_f32_dpp v34, v34, v34 row_ror:8 row_mask:0xf bank_mask:0xf bound_ctrl:1
	ds_read_b128 v[142:145], v94 offset:10032
	ds_read_b128 v[146:149], v94 offset:10288
	v_pk_fma_f32 v[28:29], v[114:115], v[34:35], v[36:37] op_sel_hi:[1,0,1] neg_lo:[0,1,0] neg_hi:[0,1,0]
	v_pk_fma_f32 v[30:31], v[116:117], v[34:35], v[38:39] op_sel_hi:[1,0,1] neg_lo:[0,1,0] neg_hi:[0,1,0]
	v_cndmask_b32_e64 v42, v42, v34, s[46:47]
	ds_read_b32 v154, v95 offset:10800
	s_waitcnt lgkmcnt(4)
	v_pk_mul_f32 v[24:25], v[30:31], v[136:137]
	v_pk_mul_f32 v[26:27], v[30:31], v[152:153]
	v_pk_fma_f32 v[24:25], v[28:29], v[134:135], v[24:25]
	v_pk_fma_f32 v[26:27], v[28:29], v[150:151], v[26:27]
	v_add_f32_e32 v34, v24, v25
	ds_read_b128 v[110:113], v94 offset:10880
	v_add_f32_e32 v57, v26, v27
	v_add_f32_dpp v34, v34, v34 quad_perm:[1,0,3,2] row_mask:0xf bank_mask:0xf bound_ctrl:1
	ds_read_b128 v[126:129], v94 offset:11904
	ds_read_b128 v[114:117], v94 offset:11136
	v_add_f32_dpp v34, v34, v34 quad_perm:[2,3,0,1] row_mask:0xf bank_mask:0xf bound_ctrl:1
	s_waitcnt lgkmcnt(3)
	v_pk_mul_f32 v[36:37], v[146:147], v[154:155] op_sel_hi:[1,0]
	v_pk_mul_f32 v[38:39], v[148:149], v[154:155] op_sel_hi:[1,0]
	v_add_f32_dpp v34, v34, v34 row_ror:4 row_mask:0xf bank_mask:0xf bound_ctrl:1
	v_pk_fma_f32 v[36:37], v[28:29], v[142:143], v[36:37]
	v_pk_fma_f32 v[38:39], v[30:31], v[144:145], v[38:39]
	v_add_f32_dpp v34, v34, v34 row_ror:8 row_mask:0xf bank_mask:0xf bound_ctrl:1
	ds_read_b128 v[118:121], v94 offset:11392
	ds_read_b128 v[122:125], v94 offset:11648
	v_pk_fma_f32 v[28:29], v[138:139], v[34:35], v[36:37] op_sel_hi:[1,0,1] neg_lo:[0,1,0] neg_hi:[0,1,0]
	v_pk_fma_f32 v[30:31], v[140:141], v[34:35], v[38:39] op_sel_hi:[1,0,1] neg_lo:[0,1,0] neg_hi:[0,1,0]
	v_cndmask_b32_e64 v42, v42, v34, s[58:59]
	ds_read_b32 v130, v95 offset:12160
	s_waitcnt lgkmcnt(4)
	v_pk_mul_f32 v[24:25], v[30:31], v[112:113]
	v_pk_mul_f32 v[26:27], v[30:31], v[128:129]
	v_pk_fma_f32 v[24:25], v[28:29], v[110:111], v[24:25]
	v_pk_fma_f32 v[26:27], v[28:29], v[126:127], v[26:27]
	v_add_f32_e32 v34, v24, v25
	ds_read_b128 v[134:137], v94 offset:12240
	v_add_f32_e32 v58, v26, v27
	v_add_f32_dpp v34, v34, v34 quad_perm:[1,0,3,2] row_mask:0xf bank_mask:0xf bound_ctrl:1
	ds_read_b128 v[150:153], v94 offset:13264
	ds_read_b128 v[138:141], v94 offset:12496
	v_add_f32_dpp v34, v34, v34 quad_perm:[2,3,0,1] row_mask:0xf bank_mask:0xf bound_ctrl:1
	s_waitcnt lgkmcnt(3)
	v_pk_mul_f32 v[36:37], v[122:123], v[130:131] op_sel_hi:[1,0]
	v_pk_mul_f32 v[38:39], v[124:125], v[130:131] op_sel_hi:[1,0]
	v_add_f32_dpp v34, v34, v34 row_ror:4 row_mask:0xf bank_mask:0xf bound_ctrl:1
	v_pk_fma_f32 v[36:37], v[28:29], v[118:119], v[36:37]
	v_pk_fma_f32 v[38:39], v[30:31], v[120:121], v[38:39]
	v_add_f32_dpp v34, v34, v34 row_ror:8 row_mask:0xf bank_mask:0xf bound_ctrl:1
	ds_read_b128 v[142:145], v94 offset:12752
	ds_read_b128 v[146:149], v94 offset:13008
	v_pk_fma_f32 v[28:29], v[114:115], v[34:35], v[36:37] op_sel_hi:[1,0,1] neg_lo:[0,1,0] neg_hi:[0,1,0]
	v_pk_fma_f32 v[30:31], v[116:117], v[34:35], v[38:39] op_sel_hi:[1,0,1] neg_lo:[0,1,0] neg_hi:[0,1,0]
	v_cndmask_b32_e64 v42, v42, v34, s[60:61]
	ds_read_b32 v154, v95 offset:13520
	s_waitcnt lgkmcnt(4)
	v_pk_mul_f32 v[24:25], v[30:31], v[136:137]
	v_pk_mul_f32 v[26:27], v[30:31], v[152:153]
	v_pk_fma_f32 v[24:25], v[28:29], v[134:135], v[24:25]
	v_pk_fma_f32 v[26:27], v[28:29], v[150:151], v[26:27]
	v_add_f32_e32 v34, v24, v25
	ds_read_b128 v[110:113], v94 offset:13600
	v_add_f32_e32 v59, v26, v27
	v_add_f32_dpp v34, v34, v34 quad_perm:[1,0,3,2] row_mask:0xf bank_mask:0xf bound_ctrl:1
	ds_read_b128 v[126:129], v94 offset:14624
	ds_read_b128 v[114:117], v94 offset:13856
	v_add_f32_dpp v34, v34, v34 quad_perm:[2,3,0,1] row_mask:0xf bank_mask:0xf bound_ctrl:1
	s_waitcnt lgkmcnt(3)
	v_pk_mul_f32 v[36:37], v[146:147], v[154:155] op_sel_hi:[1,0]
	v_pk_mul_f32 v[38:39], v[148:149], v[154:155] op_sel_hi:[1,0]
	v_add_f32_dpp v34, v34, v34 row_ror:4 row_mask:0xf bank_mask:0xf bound_ctrl:1
	v_pk_fma_f32 v[36:37], v[28:29], v[142:143], v[36:37]
	v_pk_fma_f32 v[38:39], v[30:31], v[144:145], v[38:39]
	v_add_f32_dpp v34, v34, v34 row_ror:8 row_mask:0xf bank_mask:0xf bound_ctrl:1
	ds_read_b128 v[118:121], v94 offset:14112
	ds_read_b128 v[122:125], v94 offset:14368
	v_pk_fma_f32 v[28:29], v[138:139], v[34:35], v[36:37] op_sel_hi:[1,0,1] neg_lo:[0,1,0] neg_hi:[0,1,0]
	v_pk_fma_f32 v[30:31], v[140:141], v[34:35], v[38:39] op_sel_hi:[1,0,1] neg_lo:[0,1,0] neg_hi:[0,1,0]
	v_cndmask_b32_e64 v42, v42, v34, s[62:63]
	ds_read_b32 v130, v95 offset:14880
	s_waitcnt lgkmcnt(4)
	v_pk_mul_f32 v[24:25], v[30:31], v[112:113]
	v_pk_mul_f32 v[26:27], v[30:31], v[128:129]
	v_pk_fma_f32 v[24:25], v[28:29], v[110:111], v[24:25]
	v_pk_fma_f32 v[26:27], v[28:29], v[126:127], v[26:27]
	v_add_f32_e32 v34, v24, v25
	ds_read_b128 v[134:137], v94 offset:14960
	v_add_f32_e32 v60, v26, v27
	v_add_f32_dpp v34, v34, v34 quad_perm:[1,0,3,2] row_mask:0xf bank_mask:0xf bound_ctrl:1
	ds_read_b128 v[150:153], v94 offset:15984
	ds_read_b128 v[138:141], v94 offset:15216
	v_add_f32_dpp v34, v34, v34 quad_perm:[2,3,0,1] row_mask:0xf bank_mask:0xf bound_ctrl:1
	s_waitcnt lgkmcnt(3)
	v_pk_mul_f32 v[36:37], v[122:123], v[130:131] op_sel_hi:[1,0]
	v_pk_mul_f32 v[38:39], v[124:125], v[130:131] op_sel_hi:[1,0]
	v_add_f32_dpp v34, v34, v34 row_ror:4 row_mask:0xf bank_mask:0xf bound_ctrl:1
	v_pk_fma_f32 v[36:37], v[28:29], v[118:119], v[36:37]
	v_pk_fma_f32 v[38:39], v[30:31], v[120:121], v[38:39]
	v_add_f32_dpp v34, v34, v34 row_ror:8 row_mask:0xf bank_mask:0xf bound_ctrl:1
	ds_read_b128 v[142:145], v94 offset:15472
	ds_read_b128 v[146:149], v94 offset:15728
	v_pk_fma_f32 v[28:29], v[114:115], v[34:35], v[36:37] op_sel_hi:[1,0,1] neg_lo:[0,1,0] neg_hi:[0,1,0]
	v_pk_fma_f32 v[30:31], v[116:117], v[34:35], v[38:39] op_sel_hi:[1,0,1] neg_lo:[0,1,0] neg_hi:[0,1,0]
	v_cndmask_b32_e64 v42, v42, v34, s[64:65]
	ds_read_b32 v154, v95 offset:16240
	s_waitcnt lgkmcnt(4)
	v_pk_mul_f32 v[24:25], v[30:31], v[136:137]
	v_pk_mul_f32 v[26:27], v[30:31], v[152:153]
	v_pk_fma_f32 v[24:25], v[28:29], v[134:135], v[24:25]
	v_pk_fma_f32 v[26:27], v[28:29], v[150:151], v[26:27]
	v_add_f32_e32 v34, v24, v25
	ds_read_b128 v[110:113], v94 offset:16320
	v_add_f32_e32 v61, v26, v27
	v_add_f32_dpp v34, v34, v34 quad_perm:[1,0,3,2] row_mask:0xf bank_mask:0xf bound_ctrl:1
	ds_read_b128 v[126:129], v94 offset:17344
	ds_read_b128 v[114:117], v94 offset:16576
	v_add_f32_dpp v34, v34, v34 quad_perm:[2,3,0,1] row_mask:0xf bank_mask:0xf bound_ctrl:1
	s_waitcnt lgkmcnt(3)
	v_pk_mul_f32 v[36:37], v[146:147], v[154:155] op_sel_hi:[1,0]
	v_pk_mul_f32 v[38:39], v[148:149], v[154:155] op_sel_hi:[1,0]
	v_add_f32_dpp v34, v34, v34 row_ror:4 row_mask:0xf bank_mask:0xf bound_ctrl:1
	v_pk_fma_f32 v[36:37], v[28:29], v[142:143], v[36:37]
	v_pk_fma_f32 v[38:39], v[30:31], v[144:145], v[38:39]
	v_add_f32_dpp v34, v34, v34 row_ror:8 row_mask:0xf bank_mask:0xf bound_ctrl:1
	ds_read_b128 v[118:121], v94 offset:16832
	ds_read_b128 v[122:125], v94 offset:17088
	v_pk_fma_f32 v[28:29], v[138:139], v[34:35], v[36:37] op_sel_hi:[1,0,1] neg_lo:[0,1,0] neg_hi:[0,1,0]
	v_pk_fma_f32 v[30:31], v[140:141], v[34:35], v[38:39] op_sel_hi:[1,0,1] neg_lo:[0,1,0] neg_hi:[0,1,0]
	v_cndmask_b32_e64 v42, v42, v34, s[66:67]
	ds_read_b32 v130, v95 offset:17600
	s_waitcnt lgkmcnt(4)
	v_pk_mul_f32 v[24:25], v[30:31], v[112:113]
	v_pk_mul_f32 v[26:27], v[30:31], v[128:129]
	v_pk_fma_f32 v[24:25], v[28:29], v[110:111], v[24:25]
	v_pk_fma_f32 v[26:27], v[28:29], v[126:127], v[26:27]
	v_add_f32_e32 v34, v24, v25
	ds_read_b128 v[134:137], v94 offset:17680
	v_add_f32_e32 v62, v26, v27
	v_add_f32_dpp v34, v34, v34 quad_perm:[1,0,3,2] row_mask:0xf bank_mask:0xf bound_ctrl:1
	ds_read_b128 v[150:153], v94 offset:18704
	ds_read_b128 v[138:141], v94 offset:17936
	v_add_f32_dpp v34, v34, v34 quad_perm:[2,3,0,1] row_mask:0xf bank_mask:0xf bound_ctrl:1
	s_waitcnt lgkmcnt(3)
	v_pk_mul_f32 v[36:37], v[122:123], v[130:131] op_sel_hi:[1,0]
	v_pk_mul_f32 v[38:39], v[124:125], v[130:131] op_sel_hi:[1,0]
	v_add_f32_dpp v34, v34, v34 row_ror:4 row_mask:0xf bank_mask:0xf bound_ctrl:1
	v_pk_fma_f32 v[36:37], v[28:29], v[118:119], v[36:37]
	v_pk_fma_f32 v[38:39], v[30:31], v[120:121], v[38:39]
	v_add_f32_dpp v34, v34, v34 row_ror:8 row_mask:0xf bank_mask:0xf bound_ctrl:1
	ds_read_b128 v[142:145], v94 offset:18192
	ds_read_b128 v[146:149], v94 offset:18448
	v_pk_fma_f32 v[28:29], v[114:115], v[34:35], v[36:37] op_sel_hi:[1,0,1] neg_lo:[0,1,0] neg_hi:[0,1,0]
	v_pk_fma_f32 v[30:31], v[116:117], v[34:35], v[38:39] op_sel_hi:[1,0,1] neg_lo:[0,1,0] neg_hi:[0,1,0]
	v_cndmask_b32_e64 v42, v42, v34, s[68:69]
	ds_read_b32 v154, v95 offset:18960
	s_waitcnt lgkmcnt(4)
	v_pk_mul_f32 v[24:25], v[30:31], v[136:137]
	v_pk_mul_f32 v[26:27], v[30:31], v[152:153]
	v_pk_fma_f32 v[24:25], v[28:29], v[134:135], v[24:25]
	v_pk_fma_f32 v[26:27], v[28:29], v[150:151], v[26:27]
	v_add_f32_e32 v34, v24, v25
	ds_read_b128 v[110:113], v94 offset:19040
	v_add_f32_e32 v63, v26, v27
	v_add_f32_dpp v34, v34, v34 quad_perm:[1,0,3,2] row_mask:0xf bank_mask:0xf bound_ctrl:1
	ds_read_b128 v[126:129], v94 offset:20064
	ds_read_b128 v[114:117], v94 offset:19296
	v_add_f32_dpp v34, v34, v34 quad_perm:[2,3,0,1] row_mask:0xf bank_mask:0xf bound_ctrl:1
	s_waitcnt lgkmcnt(3)
	v_pk_mul_f32 v[36:37], v[146:147], v[154:155] op_sel_hi:[1,0]
	v_pk_mul_f32 v[38:39], v[148:149], v[154:155] op_sel_hi:[1,0]
	v_add_f32_dpp v34, v34, v34 row_ror:4 row_mask:0xf bank_mask:0xf bound_ctrl:1
	v_pk_fma_f32 v[36:37], v[28:29], v[142:143], v[36:37]
	v_pk_fma_f32 v[38:39], v[30:31], v[144:145], v[38:39]
	v_add_f32_dpp v34, v34, v34 row_ror:8 row_mask:0xf bank_mask:0xf bound_ctrl:1
	ds_read_b128 v[118:121], v94 offset:19552
	ds_read_b128 v[122:125], v94 offset:19808
	v_pk_fma_f32 v[28:29], v[138:139], v[34:35], v[36:37] op_sel_hi:[1,0,1] neg_lo:[0,1,0] neg_hi:[0,1,0]
	v_pk_fma_f32 v[30:31], v[140:141], v[34:35], v[38:39] op_sel_hi:[1,0,1] neg_lo:[0,1,0] neg_hi:[0,1,0]
	v_cndmask_b32_e64 v42, v42, v34, s[76:77]
	ds_read_b32 v130, v95 offset:20320
	s_waitcnt lgkmcnt(4)
	v_pk_mul_f32 v[24:25], v[30:31], v[112:113]
	v_pk_mul_f32 v[26:27], v[30:31], v[128:129]
	v_pk_fma_f32 v[24:25], v[28:29], v[110:111], v[24:25]
	v_pk_fma_f32 v[26:27], v[28:29], v[126:127], v[26:27]
	v_add_f32_e32 v34, v24, v25
	ds_read_b128 v[134:137], v94 offset:20400
	v_add_f32_e32 v64, v26, v27
	v_add_f32_dpp v34, v34, v34 quad_perm:[1,0,3,2] row_mask:0xf bank_mask:0xf bound_ctrl:1
	ds_read_b128 v[150:153], v94 offset:21424
	ds_read_b128 v[138:141], v94 offset:20656
	v_add_f32_dpp v34, v34, v34 quad_perm:[2,3,0,1] row_mask:0xf bank_mask:0xf bound_ctrl:1
	s_waitcnt lgkmcnt(3)
	v_pk_mul_f32 v[36:37], v[122:123], v[130:131] op_sel_hi:[1,0]
	v_pk_mul_f32 v[38:39], v[124:125], v[130:131] op_sel_hi:[1,0]
	v_add_f32_dpp v34, v34, v34 row_ror:4 row_mask:0xf bank_mask:0xf bound_ctrl:1
	v_pk_fma_f32 v[36:37], v[28:29], v[118:119], v[36:37]
	v_pk_fma_f32 v[38:39], v[30:31], v[120:121], v[38:39]
	v_add_f32_dpp v34, v34, v34 row_ror:8 row_mask:0xf bank_mask:0xf bound_ctrl:1
	ds_read_b128 v[142:145], v94 offset:20912
	ds_read_b128 v[146:149], v94 offset:21168
	v_pk_fma_f32 v[28:29], v[114:115], v[34:35], v[36:37] op_sel_hi:[1,0,1] neg_lo:[0,1,0] neg_hi:[0,1,0]
	v_pk_fma_f32 v[30:31], v[116:117], v[34:35], v[38:39] op_sel_hi:[1,0,1] neg_lo:[0,1,0] neg_hi:[0,1,0]
	v_cndmask_b32_e32 v42, v42, v34, vcc
	ds_read_b32 v154, v95 offset:21680
	s_waitcnt lgkmcnt(4)
	v_pk_mul_f32 v[24:25], v[30:31], v[136:137]
	v_pk_mul_f32 v[26:27], v[30:31], v[152:153]
	v_pk_fma_f32 v[24:25], v[28:29], v[134:135], v[24:25]
	v_pk_fma_f32 v[26:27], v[28:29], v[150:151], v[26:27]
	v_add_f32_e32 v34, v24, v25
	v_lshl_add_u64 v[70:71], v[70:71], 0, s[2:3]
	v_add_f32_e32 v65, v26, v27
	v_add_f32_dpp v34, v34, v34 quad_perm:[1,0,3,2] row_mask:0xf bank_mask:0xf bound_ctrl:1
	v_lshl_add_u64 v[72:73], v[72:73], 0, s[20:21]
	v_lshl_add_u64 v[74:75], v[74:75], 0, s[20:21]
	v_add_f32_dpp v34, v34, v34 quad_perm:[2,3,0,1] row_mask:0xf bank_mask:0xf bound_ctrl:1
	s_waitcnt lgkmcnt(0)
	v_pk_mul_f32 v[36:37], v[146:147], v[154:155] op_sel_hi:[1,0]
	v_pk_mul_f32 v[38:39], v[148:149], v[154:155] op_sel_hi:[1,0]
	v_add_f32_dpp v34, v34, v34 row_ror:4 row_mask:0xf bank_mask:0xf bound_ctrl:1
	v_pk_fma_f32 v[36:37], v[28:29], v[142:143], v[36:37]
	v_pk_fma_f32 v[38:39], v[30:31], v[144:145], v[38:39]
	v_add_f32_dpp v34, v34, v34 row_ror:8 row_mask:0xf bank_mask:0xf bound_ctrl:1
	v_pk_fma_f32 v[28:29], v[138:139], v[34:35], v[36:37] op_sel_hi:[1,0,1] neg_lo:[0,1,0] neg_hi:[0,1,0]
	v_pk_fma_f32 v[30:31], v[140:141], v[34:35], v[38:39] op_sel_hi:[1,0,1] neg_lo:[0,1,0] neg_hi:[0,1,0]
	v_cndmask_b32_e64 v42, v42, v34, s[4:5]
	v_add_f32_dpp v50, v50, v50 row_ror:8 row_mask:0xf bank_mask:0xf bound_ctrl:1
	v_add_f32_dpp v51, v51, v51 row_ror:8 row_mask:0xf bank_mask:0xf bound_ctrl:1
	v_add_f32_dpp v52, v52, v52 row_ror:8 row_mask:0xf bank_mask:0xf bound_ctrl:1
	v_add_f32_dpp v53, v53, v53 row_ror:8 row_mask:0xf bank_mask:0xf bound_ctrl:1
	v_add_f32_dpp v54, v54, v54 row_ror:8 row_mask:0xf bank_mask:0xf bound_ctrl:1
	v_add_f32_dpp v55, v55, v55 row_ror:8 row_mask:0xf bank_mask:0xf bound_ctrl:1
	v_add_f32_dpp v56, v56, v56 row_ror:8 row_mask:0xf bank_mask:0xf bound_ctrl:1
	v_add_f32_dpp v57, v57, v57 row_ror:8 row_mask:0xf bank_mask:0xf bound_ctrl:1
	v_add_f32_dpp v50, v58, v58 row_ror:8 row_mask:0xf bank_mask:0xc bound_ctrl:1
	v_add_f32_dpp v51, v59, v59 row_ror:8 row_mask:0xf bank_mask:0xc bound_ctrl:1
	v_add_f32_dpp v52, v60, v60 row_ror:8 row_mask:0xf bank_mask:0xc bound_ctrl:1
	v_add_f32_dpp v53, v61, v61 row_ror:8 row_mask:0xf bank_mask:0xc bound_ctrl:1
	v_add_f32_dpp v54, v62, v62 row_ror:8 row_mask:0xf bank_mask:0xc bound_ctrl:1
	v_add_f32_dpp v55, v63, v63 row_ror:8 row_mask:0xf bank_mask:0xc bound_ctrl:1
	v_add_f32_dpp v56, v64, v64 row_ror:8 row_mask:0xf bank_mask:0xc bound_ctrl:1
	v_add_f32_dpp v57, v65, v65 row_ror:8 row_mask:0xf bank_mask:0xc bound_ctrl:1
	s_mov_b32 s2, 0xcccccccc
	s_mov_b32 s3, 0xcccccccc
	v_add_f32_dpp v50, v50, v50 row_half_mirror row_mask:0xf bank_mask:0x5 bound_ctrl:1
	v_add_f32_dpp v51, v51, v51 row_half_mirror row_mask:0xf bank_mask:0x5 bound_ctrl:1
	v_add_f32_dpp v52, v52, v52 row_half_mirror row_mask:0xf bank_mask:0x5 bound_ctrl:1
	v_add_f32_dpp v53, v53, v53 row_half_mirror row_mask:0xf bank_mask:0x5 bound_ctrl:1
	s_mov_b32 s20, 0xaaaaaaaa
	s_mov_b32 s21, 0xaaaaaaaa
	v_add_f32_dpp v50, v54, v54 row_half_mirror row_mask:0xf bank_mask:0xa bound_ctrl:1
	v_add_f32_dpp v51, v55, v55 row_half_mirror row_mask:0xf bank_mask:0xa bound_ctrl:1
	v_add_f32_dpp v52, v56, v56 row_half_mirror row_mask:0xf bank_mask:0xa bound_ctrl:1
	v_add_f32_dpp v53, v57, v57 row_half_mirror row_mask:0xf bank_mask:0xa bound_ctrl:1
	v_cndmask_b32_e64 v58, v52, v50, s[2:3]
	v_cndmask_b32_e64 v59, v53, v51, s[2:3]
	v_cndmask_b32_e64 v60, v50, v52, s[2:3]
	v_cndmask_b32_e64 v61, v51, v53, s[2:3]
	v_add_f32_dpp v50, v58, v60 quad_perm:[2,3,0,1] row_mask:0xf bank_mask:0xf bound_ctrl:1
	v_add_f32_dpp v51, v59, v61 quad_perm:[2,3,0,1] row_mask:0xf bank_mask:0xf bound_ctrl:1
	v_lshl_add_u64 v[24:25], v[68:69], 0, s[0:1]
	s_add_u32 s0, s0, 0x1000
	s_addc_u32 s1, s1, 0
	v_cndmask_b32_e64 v58, v51, v50, s[20:21]
	v_cndmask_b32_e64 v60, v50, v51, s[20:21]
	s_mov_b32 s24, s38
	s_cmp_lg_u32 s0, 0x54000
	v_add_f32_dpp v43, v58, v60 quad_perm:[1,0,3,2] row_mask:0xf bank_mask:0xf bound_ctrl:1
	v_fma_f32 v40, -v44, v42, v43
	v_fmac_f32_e32 v40, v48, v45
	global_store_dword v[24:25], v40, off
	s_barrier
	s_cbranch_scc0 .LBB0_233
